# GEMM0/GEMM1 K loops: s_setprio 2 from the first MFMA of an iteration until just before the barrier (favours the wave inside its MFMA body over its SIMD partner)
# speedup vs baseline: 1.0117x; 1.0117x over previous
.Lgq_c:
	ds_read_b128 v[114:117], v188 offset:16384
	ds_read_b128 v[118:121], v188 offset:16896
	ds_read_b128 v[156:159], v188 offset:20480
	ds_read_b128 v[160:163], v188 offset:20992
	ds_read_b128 v[122:125], v112
	ds_read_b128 v[126:129], v112 offset:2048
	s_waitcnt lgkmcnt(1)
	v_mfma_f32_16x16x32_bf16 v[66:69], v[114:117], v[122:125], v[66:69]
	s_setprio 2
	global_load_dwordx4 v[62:65], v216, s[0:1] offset:256
	v_mfma_f32_16x16x32_bf16 v[58:61], v[118:121], v[122:125], v[58:61]
	s_waitcnt vmcnt(8)
	ds_write_b128 v110, v[224:227] offset:32768
	v_mfma_f32_16x16x32_bf16 v[54:57], v[156:159], v[122:125], v[54:57]
	v_mfma_f32_16x16x32_bf16 v[50:53], v[160:163], v[122:125], v[50:53]
	global_load_dwordx4 v[70:73], v217, s[0:1] offset:256
	s_waitcnt lgkmcnt(1)
	v_mfma_f32_16x16x32_bf16 v[46:49], v[114:117], v[126:129], v[46:49]
	ds_read_b128 v[180:183], v112 offset:4096
	ds_read_b128 v[184:187], v112 offset:6144
	v_mfma_f32_16x16x32_bf16 v[42:45], v[118:121], v[126:129], v[42:45]
	s_waitcnt vmcnt(8)
	ds_write_b128 v110, v[228:231] offset:36864
	v_mfma_f32_16x16x32_bf16 v[38:41], v[156:159], v[126:129], v[38:41]
	global_load_dwordx4 v[74:77], v218, s[0:1] offset:256
	v_mfma_f32_16x16x32_bf16 v[34:37], v[160:163], v[126:129], v[34:37]
	s_waitcnt lgkmcnt(2)
	v_mfma_f32_16x16x32_bf16 v[30:33], v[114:117], v[180:183], v[30:33]
	ds_read_b128 v[164:167], v189 offset:16384
	ds_read_b128 v[168:171], v189 offset:16896
	v_mfma_f32_16x16x32_bf16 v[26:29], v[118:121], v[180:183], v[26:29]
	global_load_dwordx4 v[78:81], v219, s[0:1] offset:256
	v_mfma_f32_16x16x32_bf16 v[22:25], v[156:159], v[180:183], v[22:25]
	ds_read_b128 v[172:175], v189 offset:20480
	ds_read_b128 v[176:179], v189 offset:20992
	v_mfma_f32_16x16x32_bf16 v[18:21], v[160:163], v[180:183], v[18:21]
	s_waitcnt vmcnt(9)
	ds_write_b128 v110, v[232:235] offset:40960
	s_waitcnt lgkmcnt(6)
	v_mfma_f32_16x16x32_bf16 v[14:17], v[114:117], v[184:187], v[14:17]
	ds_read_b128 v[122:125], v113
	ds_read_b128 v[126:129], v113 offset:2048
	v_mfma_f32_16x16x32_bf16 v[10:13], v[118:121], v[184:187], v[10:13]
	global_load_dwordx4 v[82:85], v216, s[6:7] offset:256
	v_mfma_f32_16x16x32_bf16 v[6:9], v[156:159], v[184:187], v[6:9]
	s_waitcnt vmcnt(9)
	ds_write_b128 v110, v[236:239] offset:45056
	v_mfma_f32_16x16x32_bf16 v[2:5], v[160:163], v[184:187], v[2:5]
	s_waitcnt lgkmcnt(2)
	v_mfma_f32_16x16x32_bf16 v[66:69], v[164:167], v[122:125], v[66:69]
	global_load_dwordx4 v[86:89], v217, s[6:7] offset:256
	v_mfma_f32_16x16x32_bf16 v[58:61], v[168:171], v[122:125], v[58:61]
	s_waitcnt vmcnt(9)
	ds_write_b128 v190, v[240:243] offset:49168
	v_mfma_f32_16x16x32_bf16 v[54:57], v[172:175], v[122:125], v[54:57]
	v_mfma_f32_16x16x32_bf16 v[50:53], v[176:179], v[122:125], v[50:53]
	global_load_dwordx4 v[90:93], v218, s[6:7] offset:256
	s_waitcnt lgkmcnt(2)
	v_mfma_f32_16x16x32_bf16 v[46:49], v[164:167], v[126:129], v[46:49]
	ds_read_b128 v[180:183], v113 offset:4096
	ds_read_b128 v[184:187], v113 offset:6144
	v_mfma_f32_16x16x32_bf16 v[42:45], v[168:171], v[126:129], v[42:45]
	s_waitcnt vmcnt(9)
	ds_write_b128 v190, v[244:247] offset:53264
	v_mfma_f32_16x16x32_bf16 v[38:41], v[172:175], v[126:129], v[38:41]
	global_load_dwordx4 v[94:97], v219, s[6:7] offset:256
	v_mfma_f32_16x16x32_bf16 v[34:37], v[176:179], v[126:129], v[34:37]
	s_waitcnt lgkmcnt(2)
	v_mfma_f32_16x16x32_bf16 v[30:33], v[164:167], v[180:183], v[30:33]
	s_waitcnt vmcnt(9)
	ds_write_b128 v190, v[248:251] offset:57360
	v_mfma_f32_16x16x32_bf16 v[26:29], v[168:171], v[180:183], v[26:29]
	v_mfma_f32_16x16x32_bf16 v[22:25], v[172:175], v[180:183], v[22:25]
	v_mfma_f32_16x16x32_bf16 v[18:21], v[176:179], v[180:183], v[18:21]
	s_waitcnt vmcnt(8)
	ds_write_b128 v190, v[252:255] offset:61456
	s_waitcnt lgkmcnt(3)
	v_mfma_f32_16x16x32_bf16 v[14:17], v[164:167], v[184:187], v[14:17]
	v_mfma_f32_16x16x32_bf16 v[10:13], v[168:171], v[184:187], v[10:13]
	v_mfma_f32_16x16x32_bf16 v[6:9], v[172:175], v[184:187], v[6:9]
	v_mfma_f32_16x16x32_bf16 v[2:5], v[176:179], v[184:187], v[2:5]
	s_setprio 0
	s_waitcnt lgkmcnt(0)
	s_barrier
	s_add_u32 s0, s0, 0x80
	s_addc_u32 s1, s1, 0
	s_add_u32 s6, s6, 0x80
	s_addc_u32 s7, s7, 0
	ds_read_b128 v[114:117], v188 offset:49168
	ds_read_b128 v[118:121], v188 offset:49680
	ds_read_b128 v[156:159], v188 offset:53264
	ds_read_b128 v[160:163], v188 offset:53776
	ds_read_b128 v[122:125], v112 offset:32768
	ds_read_b128 v[126:129], v112 offset:34816
	s_waitcnt lgkmcnt(1)
	v_mfma_f32_16x16x32_bf16 v[66:69], v[114:117], v[122:125], v[66:69]
	s_setprio 2
	global_load_dwordx4 v[224:227], v216, s[0:1] offset:256
	v_mfma_f32_16x16x32_bf16 v[58:61], v[118:121], v[122:125], v[58:61]
	s_waitcnt vmcnt(8)
	ds_write_b128 v110, v[62:65]
	v_mfma_f32_16x16x32_bf16 v[54:57], v[156:159], v[122:125], v[54:57]
	v_mfma_f32_16x16x32_bf16 v[50:53], v[160:163], v[122:125], v[50:53]
	global_load_dwordx4 v[228:231], v217, s[0:1] offset:256
	s_waitcnt lgkmcnt(1)
	v_mfma_f32_16x16x32_bf16 v[46:49], v[114:117], v[126:129], v[46:49]
	ds_read_b128 v[180:183], v112 offset:36864
	ds_read_b128 v[184:187], v112 offset:38912
	v_mfma_f32_16x16x32_bf16 v[42:45], v[118:121], v[126:129], v[42:45]
	s_waitcnt vmcnt(8)
	ds_write_b128 v110, v[70:73] offset:4096
	v_mfma_f32_16x16x32_bf16 v[38:41], v[156:159], v[126:129], v[38:41]
	global_load_dwordx4 v[232:235], v218, s[0:1] offset:256
	v_mfma_f32_16x16x32_bf16 v[34:37], v[160:163], v[126:129], v[34:37]
	s_waitcnt lgkmcnt(2)
	v_mfma_f32_16x16x32_bf16 v[30:33], v[114:117], v[180:183], v[30:33]
	ds_read_b128 v[164:167], v189 offset:49168
	ds_read_b128 v[168:171], v189 offset:49680
	v_mfma_f32_16x16x32_bf16 v[26:29], v[118:121], v[180:183], v[26:29]
	global_load_dwordx4 v[236:239], v219, s[0:1] offset:256
	v_mfma_f32_16x16x32_bf16 v[22:25], v[156:159], v[180:183], v[22:25]
	ds_read_b128 v[172:175], v189 offset:53264
	ds_read_b128 v[176:179], v189 offset:53776
	v_mfma_f32_16x16x32_bf16 v[18:21], v[160:163], v[180:183], v[18:21]
	s_waitcnt vmcnt(9)
	ds_write_b128 v110, v[74:77] offset:8192
	s_waitcnt lgkmcnt(6)
	v_mfma_f32_16x16x32_bf16 v[14:17], v[114:117], v[184:187], v[14:17]
	ds_read_b128 v[122:125], v113 offset:32768
	ds_read_b128 v[126:129], v113 offset:34816
	v_mfma_f32_16x16x32_bf16 v[10:13], v[118:121], v[184:187], v[10:13]
	global_load_dwordx4 v[240:243], v216, s[6:7] offset:256
	v_mfma_f32_16x16x32_bf16 v[6:9], v[156:159], v[184:187], v[6:9]
	s_waitcnt vmcnt(9)
	ds_write_b128 v110, v[78:81] offset:12288
	v_mfma_f32_16x16x32_bf16 v[2:5], v[160:163], v[184:187], v[2:5]
	s_waitcnt lgkmcnt(2)
	v_mfma_f32_16x16x32_bf16 v[66:69], v[164:167], v[122:125], v[66:69]
	global_load_dwordx4 v[244:247], v217, s[6:7] offset:256
	v_mfma_f32_16x16x32_bf16 v[58:61], v[168:171], v[122:125], v[58:61]
	s_waitcnt vmcnt(9)
	ds_write_b128 v190, v[82:85] offset:16384
	v_mfma_f32_16x16x32_bf16 v[54:57], v[172:175], v[122:125], v[54:57]
	v_mfma_f32_16x16x32_bf16 v[50:53], v[176:179], v[122:125], v[50:53]
	global_load_dwordx4 v[248:251], v218, s[6:7] offset:256
	s_waitcnt lgkmcnt(2)
	v_mfma_f32_16x16x32_bf16 v[46:49], v[164:167], v[126:129], v[46:49]
	ds_read_b128 v[180:183], v113 offset:36864
	ds_read_b128 v[184:187], v113 offset:38912
	v_mfma_f32_16x16x32_bf16 v[42:45], v[168:171], v[126:129], v[42:45]
	s_waitcnt vmcnt(9)
	ds_write_b128 v190, v[86:89] offset:20480
	v_mfma_f32_16x16x32_bf16 v[38:41], v[172:175], v[126:129], v[38:41]
	global_load_dwordx4 v[252:255], v219, s[6:7] offset:256
	v_mfma_f32_16x16x32_bf16 v[34:37], v[176:179], v[126:129], v[34:37]
	s_waitcnt lgkmcnt(2)
	v_mfma_f32_16x16x32_bf16 v[30:33], v[164:167], v[180:183], v[30:33]
	s_waitcnt vmcnt(9)
	ds_write_b128 v190, v[90:93] offset:24576
	v_mfma_f32_16x16x32_bf16 v[26:29], v[168:171], v[180:183], v[26:29]
	v_mfma_f32_16x16x32_bf16 v[22:25], v[172:175], v[180:183], v[22:25]
	v_mfma_f32_16x16x32_bf16 v[18:21], v[176:179], v[180:183], v[18:21]
	s_waitcnt vmcnt(8)
	ds_write_b128 v190, v[94:97] offset:28672
	s_waitcnt lgkmcnt(3)
	v_mfma_f32_16x16x32_bf16 v[14:17], v[164:167], v[184:187], v[14:17]
	v_mfma_f32_16x16x32_bf16 v[10:13], v[168:171], v[184:187], v[10:13]
	v_mfma_f32_16x16x32_bf16 v[6:9], v[172:175], v[184:187], v[6:9]
	v_mfma_f32_16x16x32_bf16 v[2:5], v[176:179], v[184:187], v[2:5]
	s_setprio 0
	s_waitcnt lgkmcnt(0)
	s_barrier
	s_add_u32 s0, s0, 0x80
	s_addc_u32 s1, s1, 0
	s_add_u32 s6, s6, 0x80
	s_addc_u32 s7, s7, 0
	s_sub_i32 vcc_lo, vcc_lo, 1
	s_cmp_lg_u32 vcc_lo, 0
	s_cbranch_scc1 .Lgq_c
	ds_read_b128 v[114:117], v188 offset:16384
	ds_read_b128 v[118:121], v188 offset:16896
	ds_read_b128 v[156:159], v188 offset:20480
	ds_read_b128 v[160:163], v188 offset:20992
	ds_read_b128 v[122:125], v112
	ds_read_b128 v[126:129], v112 offset:2048
	s_waitcnt lgkmcnt(1)
	v_mfma_f32_16x16x32_bf16 v[66:69], v[114:117], v[122:125], v[66:69]
	s_setprio 2
	v_mfma_f32_16x16x32_bf16 v[58:61], v[118:121], v[122:125], v[58:61]
	s_waitcnt vmcnt(7)
	ds_write_b128 v110, v[224:227] offset:32768
	v_mfma_f32_16x16x32_bf16 v[54:57], v[156:159], v[122:125], v[54:57]
	v_mfma_f32_16x16x32_bf16 v[50:53], v[160:163], v[122:125], v[50:53]
	s_waitcnt lgkmcnt(1)
	v_mfma_f32_16x16x32_bf16 v[46:49], v[114:117], v[126:129], v[46:49]
	ds_read_b128 v[180:183], v112 offset:4096
	ds_read_b128 v[184:187], v112 offset:6144
	v_mfma_f32_16x16x32_bf16 v[42:45], v[118:121], v[126:129], v[42:45]
	s_waitcnt vmcnt(6)
	ds_write_b128 v110, v[228:231] offset:36864
	v_mfma_f32_16x16x32_bf16 v[38:41], v[156:159], v[126:129], v[38:41]
	v_mfma_f32_16x16x32_bf16 v[34:37], v[160:163], v[126:129], v[34:37]
	s_waitcnt lgkmcnt(2)
	v_mfma_f32_16x16x32_bf16 v[30:33], v[114:117], v[180:183], v[30:33]
	ds_read_b128 v[164:167], v189 offset:16384
	ds_read_b128 v[168:171], v189 offset:16896
	v_mfma_f32_16x16x32_bf16 v[26:29], v[118:121], v[180:183], v[26:29]
	v_mfma_f32_16x16x32_bf16 v[22:25], v[156:159], v[180:183], v[22:25]
	ds_read_b128 v[172:175], v189 offset:20480
	ds_read_b128 v[176:179], v189 offset:20992
	v_mfma_f32_16x16x32_bf16 v[18:21], v[160:163], v[180:183], v[18:21]
	s_waitcnt vmcnt(5)
	ds_write_b128 v110, v[232:235] offset:40960
	s_waitcnt lgkmcnt(6)
	v_mfma_f32_16x16x32_bf16 v[14:17], v[114:117], v[184:187], v[14:17]
	ds_read_b128 v[122:125], v113
	ds_read_b128 v[126:129], v113 offset:2048
	v_mfma_f32_16x16x32_bf16 v[10:13], v[118:121], v[184:187], v[10:13]
	v_mfma_f32_16x16x32_bf16 v[6:9], v[156:159], v[184:187], v[6:9]
	s_waitcnt vmcnt(4)
	ds_write_b128 v110, v[236:239] offset:45056
	v_mfma_f32_16x16x32_bf16 v[2:5], v[160:163], v[184:187], v[2:5]
	s_waitcnt lgkmcnt(2)
	v_mfma_f32_16x16x32_bf16 v[66:69], v[164:167], v[122:125], v[66:69]
	v_mfma_f32_16x16x32_bf16 v[58:61], v[168:171], v[122:125], v[58:61]
	s_waitcnt vmcnt(3)
	ds_write_b128 v190, v[240:243] offset:49168
	v_mfma_f32_16x16x32_bf16 v[54:57], v[172:175], v[122:125], v[54:57]
	v_mfma_f32_16x16x32_bf16 v[50:53], v[176:179], v[122:125], v[50:53]
	s_waitcnt lgkmcnt(2)
	v_mfma_f32_16x16x32_bf16 v[46:49], v[164:167], v[126:129], v[46:49]
	ds_read_b128 v[180:183], v113 offset:4096
	ds_read_b128 v[184:187], v113 offset:6144
	v_mfma_f32_16x16x32_bf16 v[42:45], v[168:171], v[126:129], v[42:45]
	s_waitcnt vmcnt(2)
	ds_write_b128 v190, v[244:247] offset:53264
	v_mfma_f32_16x16x32_bf16 v[38:41], v[172:175], v[126:129], v[38:41]
	v_mfma_f32_16x16x32_bf16 v[34:37], v[176:179], v[126:129], v[34:37]
	s_waitcnt lgkmcnt(2)
	v_mfma_f32_16x16x32_bf16 v[30:33], v[164:167], v[180:183], v[30:33]
	s_waitcnt vmcnt(1)
	ds_write_b128 v190, v[248:251] offset:57360
	v_mfma_f32_16x16x32_bf16 v[26:29], v[168:171], v[180:183], v[26:29]
	v_mfma_f32_16x16x32_bf16 v[22:25], v[172:175], v[180:183], v[22:25]
	v_mfma_f32_16x16x32_bf16 v[18:21], v[176:179], v[180:183], v[18:21]
	s_waitcnt vmcnt(0)
	ds_write_b128 v190, v[252:255] offset:61456
	s_waitcnt lgkmcnt(3)
	v_mfma_f32_16x16x32_bf16 v[14:17], v[164:167], v[184:187], v[14:17]
	v_mfma_f32_16x16x32_bf16 v[10:13], v[168:171], v[184:187], v[10:13]
	v_mfma_f32_16x16x32_bf16 v[6:9], v[172:175], v[184:187], v[6:9]
	v_mfma_f32_16x16x32_bf16 v[2:5], v[176:179], v[184:187], v[2:5]
	s_waitcnt lgkmcnt(0)
	s_barrier
	ds_read_b128 v[114:117], v188 offset:49168
	ds_read_b128 v[118:121], v188 offset:49680
	ds_read_b128 v[156:159], v188 offset:53264
	ds_read_b128 v[160:163], v188 offset:53776
	ds_read_b128 v[122:125], v112 offset:32768
	ds_read_b128 v[126:129], v112 offset:34816
	s_waitcnt lgkmcnt(1)
	v_mfma_f32_16x16x32_bf16 v[66:69], v[114:117], v[122:125], v[66:69]
	s_setprio 2
	v_mfma_f32_16x16x32_bf16 v[58:61], v[118:121], v[122:125], v[58:61]
	v_mfma_f32_16x16x32_bf16 v[54:57], v[156:159], v[122:125], v[54:57]
	v_mfma_f32_16x16x32_bf16 v[50:53], v[160:163], v[122:125], v[50:53]
	s_waitcnt lgkmcnt(0)
	v_mfma_f32_16x16x32_bf16 v[46:49], v[114:117], v[126:129], v[46:49]
	ds_read_b128 v[180:183], v112 offset:36864
	ds_read_b128 v[184:187], v112 offset:38912
	v_mfma_f32_16x16x32_bf16 v[42:45], v[118:121], v[126:129], v[42:45]
	v_mfma_f32_16x16x32_bf16 v[38:41], v[156:159], v[126:129], v[38:41]
	v_mfma_f32_16x16x32_bf16 v[34:37], v[160:163], v[126:129], v[34:37]
	s_waitcnt lgkmcnt(1)
	v_mfma_f32_16x16x32_bf16 v[30:33], v[114:117], v[180:183], v[30:33]
	ds_read_b128 v[164:167], v189 offset:49168
	ds_read_b128 v[168:171], v189 offset:49680
	v_mfma_f32_16x16x32_bf16 v[26:29], v[118:121], v[180:183], v[26:29]
	v_mfma_f32_16x16x32_bf16 v[22:25], v[156:159], v[180:183], v[22:25]
	ds_read_b128 v[172:175], v189 offset:53264
	ds_read_b128 v[176:179], v189 offset:53776
	v_mfma_f32_16x16x32_bf16 v[18:21], v[160:163], v[180:183], v[18:21]
	s_waitcnt lgkmcnt(4)
	v_mfma_f32_16x16x32_bf16 v[14:17], v[114:117], v[184:187], v[14:17]
	ds_read_b128 v[122:125], v113 offset:32768
	ds_read_b128 v[126:129], v113 offset:34816
	v_mfma_f32_16x16x32_bf16 v[10:13], v[118:121], v[184:187], v[10:13]
	v_mfma_f32_16x16x32_bf16 v[6:9], v[156:159], v[184:187], v[6:9]
	v_mfma_f32_16x16x32_bf16 v[2:5], v[160:163], v[184:187], v[2:5]
	s_waitcnt lgkmcnt(1)
	v_mfma_f32_16x16x32_bf16 v[66:69], v[164:167], v[122:125], v[66:69]
	v_mfma_f32_16x16x32_bf16 v[58:61], v[168:171], v[122:125], v[58:61]
	v_mfma_f32_16x16x32_bf16 v[54:57], v[172:175], v[122:125], v[54:57]
	v_mfma_f32_16x16x32_bf16 v[50:53], v[176:179], v[122:125], v[50:53]
	s_waitcnt lgkmcnt(0)
	v_mfma_f32_16x16x32_bf16 v[46:49], v[164:167], v[126:129], v[46:49]
	ds_read_b128 v[180:183], v113 offset:36864
	ds_read_b128 v[184:187], v113 offset:38912
	v_mfma_f32_16x16x32_bf16 v[42:45], v[168:171], v[126:129], v[42:45]
	v_mfma_f32_16x16x32_bf16 v[38:41], v[172:175], v[126:129], v[38:41]
	v_mfma_f32_16x16x32_bf16 v[34:37], v[176:179], v[126:129], v[34:37]
	s_waitcnt lgkmcnt(1)
	v_mfma_f32_16x16x32_bf16 v[30:33], v[164:167], v[180:183], v[30:33]
	v_mfma_f32_16x16x32_bf16 v[26:29], v[168:171], v[180:183], v[26:29]
	v_mfma_f32_16x16x32_bf16 v[22:25], v[172:175], v[180:183], v[22:25]
	v_mfma_f32_16x16x32_bf16 v[18:21], v[176:179], v[180:183], v[18:21]
	s_waitcnt lgkmcnt(0)
	v_mfma_f32_16x16x32_bf16 v[14:17], v[164:167], v[184:187], v[14:17]
	v_mfma_f32_16x16x32_bf16 v[10:13], v[168:171], v[184:187], v[10:13]
	v_mfma_f32_16x16x32_bf16 v[6:9], v[172:175], v[184:187], v[6:9]
	v_mfma_f32_16x16x32_bf16 v[2:5], v[176:179], v[184:187], v[2:5]
	s_setprio 0
	s_barrier

.Lgq_o:
	ds_read_b128 v[114:117], v188 offset:16384
	ds_read_b128 v[122:125], v188 offset:16896
	ds_read_b128 v[126:129], v188 offset:20480
	ds_read_b128 v[156:159], v188 offset:20992
	ds_read_b128 v[118:121], v112
	ds_read_b128 v[160:163], v112 offset:2048
	s_waitcnt lgkmcnt(1)
	v_mfma_f32_16x16x32_bf16 v[94:97], v[114:117], v[118:121], v[94:97]
	s_setprio 2
	global_load_dwordx4 v[2:5], v216, s[10:11] offset:256
	v_mfma_f32_16x16x32_bf16 v[90:93], v[122:125], v[118:121], v[90:93]
	s_waitcnt vmcnt(8)
	ds_write_b128 v108, v[224:227] offset:32768
	v_mfma_f32_16x16x32_bf16 v[86:89], v[126:129], v[118:121], v[86:89]
	v_mfma_f32_16x16x32_bf16 v[82:85], v[156:159], v[118:121], v[82:85]
	global_load_dwordx4 v[6:9], v217, s[10:11] offset:256
	s_waitcnt lgkmcnt(1)
	v_mfma_f32_16x16x32_bf16 v[78:81], v[114:117], v[160:163], v[78:81]
	ds_read_b128 v[180:183], v112 offset:4096
	ds_read_b128 v[184:187], v112 offset:6144
	v_mfma_f32_16x16x32_bf16 v[74:77], v[122:125], v[160:163], v[74:77]
	s_waitcnt vmcnt(8)
	ds_write_b128 v108, v[228:231] offset:36864
	v_mfma_f32_16x16x32_bf16 v[70:73], v[126:129], v[160:163], v[70:73]
	global_load_dwordx4 v[10:13], v218, s[10:11] offset:256
	v_mfma_f32_16x16x32_bf16 v[66:69], v[156:159], v[160:163], v[66:69]
	s_waitcnt lgkmcnt(2)
	v_mfma_f32_16x16x32_bf16 v[62:65], v[114:117], v[180:183], v[62:65]
	ds_read_b128 v[164:167], v189 offset:16384
	ds_read_b128 v[168:171], v189 offset:16896
	v_mfma_f32_16x16x32_bf16 v[58:61], v[122:125], v[180:183], v[58:61]
	global_load_dwordx4 v[14:17], v219, s[10:11] offset:256
	v_mfma_f32_16x16x32_bf16 v[54:57], v[126:129], v[180:183], v[54:57]
	ds_read_b128 v[172:175], v189 offset:20480
	ds_read_b128 v[176:179], v189 offset:20992
	v_mfma_f32_16x16x32_bf16 v[50:53], v[156:159], v[180:183], v[50:53]
	s_waitcnt vmcnt(9)
	ds_write_b128 v108, v[232:235] offset:40960
	s_waitcnt lgkmcnt(6)
	v_mfma_f32_16x16x32_bf16 v[46:49], v[114:117], v[184:187], v[46:49]
	ds_read_b128 v[118:121], v113
	ds_read_b128 v[160:163], v113 offset:2048
	v_mfma_f32_16x16x32_bf16 v[42:45], v[122:125], v[184:187], v[42:45]
	global_load_dwordx4 v[18:21], v216, s[28:29] offset:256
	v_mfma_f32_16x16x32_bf16 v[38:41], v[126:129], v[184:187], v[38:41]
	s_waitcnt vmcnt(9)
	ds_write_b128 v108, v[236:239] offset:45056
	v_mfma_f32_16x16x32_bf16 v[34:37], v[156:159], v[184:187], v[34:37]
	s_waitcnt lgkmcnt(2)
	v_mfma_f32_16x16x32_bf16 v[94:97], v[164:167], v[118:121], v[94:97]
	global_load_dwordx4 v[22:25], v217, s[28:29] offset:256
	v_mfma_f32_16x16x32_bf16 v[90:93], v[168:171], v[118:121], v[90:93]
	s_waitcnt vmcnt(9)
	ds_write_b128 v190, v[240:243] offset:49168
	v_mfma_f32_16x16x32_bf16 v[86:89], v[172:175], v[118:121], v[86:89]
	v_mfma_f32_16x16x32_bf16 v[82:85], v[176:179], v[118:121], v[82:85]
	global_load_dwordx4 v[26:29], v218, s[28:29] offset:256
	s_waitcnt lgkmcnt(2)
	v_mfma_f32_16x16x32_bf16 v[78:81], v[164:167], v[160:163], v[78:81]
	ds_read_b128 v[180:183], v113 offset:4096
	ds_read_b128 v[184:187], v113 offset:6144
	v_mfma_f32_16x16x32_bf16 v[74:77], v[168:171], v[160:163], v[74:77]
	s_waitcnt vmcnt(9)
	ds_write_b128 v190, v[244:247] offset:53264
	v_mfma_f32_16x16x32_bf16 v[70:73], v[172:175], v[160:163], v[70:73]
	global_load_dwordx4 v[30:33], v219, s[28:29] offset:256
	v_mfma_f32_16x16x32_bf16 v[66:69], v[176:179], v[160:163], v[66:69]
	s_waitcnt lgkmcnt(2)
	v_mfma_f32_16x16x32_bf16 v[62:65], v[164:167], v[180:183], v[62:65]
	s_waitcnt vmcnt(9)
	ds_write_b128 v190, v[248:251] offset:57360
	v_mfma_f32_16x16x32_bf16 v[58:61], v[168:171], v[180:183], v[58:61]
	v_mfma_f32_16x16x32_bf16 v[54:57], v[172:175], v[180:183], v[54:57]
	v_mfma_f32_16x16x32_bf16 v[50:53], v[176:179], v[180:183], v[50:53]
	s_waitcnt vmcnt(8)
	ds_write_b128 v190, v[252:255] offset:61456
	s_waitcnt lgkmcnt(3)
	v_mfma_f32_16x16x32_bf16 v[46:49], v[164:167], v[184:187], v[46:49]
	v_mfma_f32_16x16x32_bf16 v[42:45], v[168:171], v[184:187], v[42:45]
	v_mfma_f32_16x16x32_bf16 v[38:41], v[172:175], v[184:187], v[38:41]
	v_mfma_f32_16x16x32_bf16 v[34:37], v[176:179], v[184:187], v[34:37]
	s_setprio 0
	s_waitcnt lgkmcnt(0)
	s_barrier
	s_add_u32 s10, s10, 0x80
	s_addc_u32 s11, s11, 0
	s_add_u32 s28, s28, 0x80
	s_addc_u32 s29, s29, 0
	ds_read_b128 v[114:117], v188 offset:49168
	ds_read_b128 v[122:125], v188 offset:49680
	ds_read_b128 v[126:129], v188 offset:53264
	ds_read_b128 v[156:159], v188 offset:53776
	ds_read_b128 v[118:121], v112 offset:32768
	ds_read_b128 v[160:163], v112 offset:34816
	s_waitcnt lgkmcnt(1)
	v_mfma_f32_16x16x32_bf16 v[94:97], v[114:117], v[118:121], v[94:97]
	s_setprio 2
	global_load_dwordx4 v[224:227], v216, s[10:11] offset:256
	v_mfma_f32_16x16x32_bf16 v[90:93], v[122:125], v[118:121], v[90:93]
	s_waitcnt vmcnt(8)
	ds_write_b128 v108, v[2:5]
	v_mfma_f32_16x16x32_bf16 v[86:89], v[126:129], v[118:121], v[86:89]
	v_mfma_f32_16x16x32_bf16 v[82:85], v[156:159], v[118:121], v[82:85]
	global_load_dwordx4 v[228:231], v217, s[10:11] offset:256
	s_waitcnt lgkmcnt(1)
	v_mfma_f32_16x16x32_bf16 v[78:81], v[114:117], v[160:163], v[78:81]
	ds_read_b128 v[180:183], v112 offset:36864
	ds_read_b128 v[184:187], v112 offset:38912
	v_mfma_f32_16x16x32_bf16 v[74:77], v[122:125], v[160:163], v[74:77]
	s_waitcnt vmcnt(8)
	ds_write_b128 v108, v[6:9] offset:4096
	v_mfma_f32_16x16x32_bf16 v[70:73], v[126:129], v[160:163], v[70:73]
	global_load_dwordx4 v[232:235], v218, s[10:11] offset:256
	v_mfma_f32_16x16x32_bf16 v[66:69], v[156:159], v[160:163], v[66:69]
	s_waitcnt lgkmcnt(2)
	v_mfma_f32_16x16x32_bf16 v[62:65], v[114:117], v[180:183], v[62:65]
	ds_read_b128 v[164:167], v189 offset:49168
	ds_read_b128 v[168:171], v189 offset:49680
	v_mfma_f32_16x16x32_bf16 v[58:61], v[122:125], v[180:183], v[58:61]
	global_load_dwordx4 v[236:239], v219, s[10:11] offset:256
	v_mfma_f32_16x16x32_bf16 v[54:57], v[126:129], v[180:183], v[54:57]
	ds_read_b128 v[172:175], v189 offset:53264
	ds_read_b128 v[176:179], v189 offset:53776
	v_mfma_f32_16x16x32_bf16 v[50:53], v[156:159], v[180:183], v[50:53]
	s_waitcnt vmcnt(9)
	ds_write_b128 v108, v[10:13] offset:8192
	s_waitcnt lgkmcnt(6)
	v_mfma_f32_16x16x32_bf16 v[46:49], v[114:117], v[184:187], v[46:49]
	ds_read_b128 v[118:121], v113 offset:32768
	ds_read_b128 v[160:163], v113 offset:34816
	v_mfma_f32_16x16x32_bf16 v[42:45], v[122:125], v[184:187], v[42:45]
	global_load_dwordx4 v[240:243], v216, s[28:29] offset:256
	v_mfma_f32_16x16x32_bf16 v[38:41], v[126:129], v[184:187], v[38:41]
	s_waitcnt vmcnt(9)
	ds_write_b128 v108, v[14:17] offset:12288
	v_mfma_f32_16x16x32_bf16 v[34:37], v[156:159], v[184:187], v[34:37]
	s_waitcnt lgkmcnt(2)
	v_mfma_f32_16x16x32_bf16 v[94:97], v[164:167], v[118:121], v[94:97]
	global_load_dwordx4 v[244:247], v217, s[28:29] offset:256
	v_mfma_f32_16x16x32_bf16 v[90:93], v[168:171], v[118:121], v[90:93]
	s_waitcnt vmcnt(9)
	ds_write_b128 v190, v[18:21] offset:16384
	v_mfma_f32_16x16x32_bf16 v[86:89], v[172:175], v[118:121], v[86:89]
	v_mfma_f32_16x16x32_bf16 v[82:85], v[176:179], v[118:121], v[82:85]
	global_load_dwordx4 v[248:251], v218, s[28:29] offset:256
	s_waitcnt lgkmcnt(2)
	v_mfma_f32_16x16x32_bf16 v[78:81], v[164:167], v[160:163], v[78:81]
	ds_read_b128 v[180:183], v113 offset:36864
	ds_read_b128 v[184:187], v113 offset:38912
	v_mfma_f32_16x16x32_bf16 v[74:77], v[168:171], v[160:163], v[74:77]
	s_waitcnt vmcnt(9)
	ds_write_b128 v190, v[22:25] offset:20480
	v_mfma_f32_16x16x32_bf16 v[70:73], v[172:175], v[160:163], v[70:73]
	global_load_dwordx4 v[252:255], v219, s[28:29] offset:256
	v_mfma_f32_16x16x32_bf16 v[66:69], v[176:179], v[160:163], v[66:69]
	s_waitcnt lgkmcnt(2)
	v_mfma_f32_16x16x32_bf16 v[62:65], v[164:167], v[180:183], v[62:65]
	s_waitcnt vmcnt(9)
	ds_write_b128 v190, v[26:29] offset:24576
	v_mfma_f32_16x16x32_bf16 v[58:61], v[168:171], v[180:183], v[58:61]
	v_mfma_f32_16x16x32_bf16 v[54:57], v[172:175], v[180:183], v[54:57]
	v_mfma_f32_16x16x32_bf16 v[50:53], v[176:179], v[180:183], v[50:53]
	s_waitcnt vmcnt(8)
	ds_write_b128 v190, v[30:33] offset:28672
	s_waitcnt lgkmcnt(3)
	v_mfma_f32_16x16x32_bf16 v[46:49], v[164:167], v[184:187], v[46:49]
	v_mfma_f32_16x16x32_bf16 v[42:45], v[168:171], v[184:187], v[42:45]
	v_mfma_f32_16x16x32_bf16 v[38:41], v[172:175], v[184:187], v[38:41]
	v_mfma_f32_16x16x32_bf16 v[34:37], v[176:179], v[184:187], v[34:37]
	s_setprio 0
	s_waitcnt lgkmcnt(0)
	s_barrier
	s_add_u32 s10, s10, 0x80
	s_addc_u32 s11, s11, 0
	s_add_u32 s28, s28, 0x80
	s_addc_u32 s29, s29, 0
	s_sub_i32 vcc_lo, vcc_lo, 1
	s_cmp_lg_u32 vcc_lo, 0
	s_cbranch_scc1 .Lgq_o
	ds_read_b128 v[114:117], v188 offset:16384
	ds_read_b128 v[122:125], v188 offset:16896
	ds_read_b128 v[126:129], v188 offset:20480
	ds_read_b128 v[156:159], v188 offset:20992
	ds_read_b128 v[118:121], v112
	ds_read_b128 v[160:163], v112 offset:2048
	s_waitcnt lgkmcnt(1)
	v_mfma_f32_16x16x32_bf16 v[94:97], v[114:117], v[118:121], v[94:97]
	s_setprio 2
	v_mfma_f32_16x16x32_bf16 v[90:93], v[122:125], v[118:121], v[90:93]
	s_waitcnt vmcnt(7)
	ds_write_b128 v108, v[224:227] offset:32768
	v_mfma_f32_16x16x32_bf16 v[86:89], v[126:129], v[118:121], v[86:89]
	v_mfma_f32_16x16x32_bf16 v[82:85], v[156:159], v[118:121], v[82:85]
	s_waitcnt lgkmcnt(1)
	v_mfma_f32_16x16x32_bf16 v[78:81], v[114:117], v[160:163], v[78:81]
	ds_read_b128 v[180:183], v112 offset:4096
	ds_read_b128 v[184:187], v112 offset:6144
	v_mfma_f32_16x16x32_bf16 v[74:77], v[122:125], v[160:163], v[74:77]
	s_waitcnt vmcnt(6)
	ds_write_b128 v108, v[228:231] offset:36864
	v_mfma_f32_16x16x32_bf16 v[70:73], v[126:129], v[160:163], v[70:73]
	v_mfma_f32_16x16x32_bf16 v[66:69], v[156:159], v[160:163], v[66:69]
	s_waitcnt lgkmcnt(2)
	v_mfma_f32_16x16x32_bf16 v[62:65], v[114:117], v[180:183], v[62:65]
	ds_read_b128 v[164:167], v189 offset:16384
	ds_read_b128 v[168:171], v189 offset:16896
	v_mfma_f32_16x16x32_bf16 v[58:61], v[122:125], v[180:183], v[58:61]
	v_mfma_f32_16x16x32_bf16 v[54:57], v[126:129], v[180:183], v[54:57]
	ds_read_b128 v[172:175], v189 offset:20480
	ds_read_b128 v[176:179], v189 offset:20992
	v_mfma_f32_16x16x32_bf16 v[50:53], v[156:159], v[180:183], v[50:53]
	s_waitcnt vmcnt(5)
	ds_write_b128 v108, v[232:235] offset:40960
	s_waitcnt lgkmcnt(6)
	v_mfma_f32_16x16x32_bf16 v[46:49], v[114:117], v[184:187], v[46:49]
	ds_read_b128 v[118:121], v113
	ds_read_b128 v[160:163], v113 offset:2048
	v_mfma_f32_16x16x32_bf16 v[42:45], v[122:125], v[184:187], v[42:45]
	v_mfma_f32_16x16x32_bf16 v[38:41], v[126:129], v[184:187], v[38:41]
	s_waitcnt vmcnt(4)
	ds_write_b128 v108, v[236:239] offset:45056
	v_mfma_f32_16x16x32_bf16 v[34:37], v[156:159], v[184:187], v[34:37]
	s_waitcnt lgkmcnt(2)
	v_mfma_f32_16x16x32_bf16 v[94:97], v[164:167], v[118:121], v[94:97]
	v_mfma_f32_16x16x32_bf16 v[90:93], v[168:171], v[118:121], v[90:93]
	s_waitcnt vmcnt(3)
	ds_write_b128 v190, v[240:243] offset:49168
	v_mfma_f32_16x16x32_bf16 v[86:89], v[172:175], v[118:121], v[86:89]
	v_mfma_f32_16x16x32_bf16 v[82:85], v[176:179], v[118:121], v[82:85]
	s_waitcnt lgkmcnt(2)
	v_mfma_f32_16x16x32_bf16 v[78:81], v[164:167], v[160:163], v[78:81]
	ds_read_b128 v[180:183], v113 offset:4096
	ds_read_b128 v[184:187], v113 offset:6144
	v_mfma_f32_16x16x32_bf16 v[74:77], v[168:171], v[160:163], v[74:77]
	s_waitcnt vmcnt(2)
	ds_write_b128 v190, v[244:247] offset:53264
	v_mfma_f32_16x16x32_bf16 v[70:73], v[172:175], v[160:163], v[70:73]
	v_mfma_f32_16x16x32_bf16 v[66:69], v[176:179], v[160:163], v[66:69]
	s_waitcnt lgkmcnt(2)
	v_mfma_f32_16x16x32_bf16 v[62:65], v[164:167], v[180:183], v[62:65]
	s_waitcnt vmcnt(1)
	ds_write_b128 v190, v[248:251] offset:57360
	v_mfma_f32_16x16x32_bf16 v[58:61], v[168:171], v[180:183], v[58:61]
	v_mfma_f32_16x16x32_bf16 v[54:57], v[172:175], v[180:183], v[54:57]
	v_mfma_f32_16x16x32_bf16 v[50:53], v[176:179], v[180:183], v[50:53]
	s_waitcnt vmcnt(0)
	ds_write_b128 v190, v[252:255] offset:61456
	s_waitcnt lgkmcnt(3)
	v_mfma_f32_16x16x32_bf16 v[46:49], v[164:167], v[184:187], v[46:49]
	v_mfma_f32_16x16x32_bf16 v[42:45], v[168:171], v[184:187], v[42:45]
	v_mfma_f32_16x16x32_bf16 v[38:41], v[172:175], v[184:187], v[38:41]
	v_mfma_f32_16x16x32_bf16 v[34:37], v[176:179], v[184:187], v[34:37]
	s_waitcnt lgkmcnt(0)
	s_barrier
	ds_read_b128 v[114:117], v188 offset:49168
	ds_read_b128 v[122:125], v188 offset:49680
	ds_read_b128 v[126:129], v188 offset:53264
	ds_read_b128 v[156:159], v188 offset:53776
	ds_read_b128 v[118:121], v112 offset:32768
	ds_read_b128 v[160:163], v112 offset:34816
	s_waitcnt lgkmcnt(1)
	v_mfma_f32_16x16x32_bf16 v[94:97], v[114:117], v[118:121], v[94:97]
	s_setprio 2
	v_mfma_f32_16x16x32_bf16 v[90:93], v[122:125], v[118:121], v[90:93]
	v_mfma_f32_16x16x32_bf16 v[86:89], v[126:129], v[118:121], v[86:89]
	v_mfma_f32_16x16x32_bf16 v[82:85], v[156:159], v[118:121], v[82:85]
	s_waitcnt lgkmcnt(0)
	v_mfma_f32_16x16x32_bf16 v[78:81], v[114:117], v[160:163], v[78:81]
	ds_read_b128 v[180:183], v112 offset:36864
	ds_read_b128 v[184:187], v112 offset:38912
	v_mfma_f32_16x16x32_bf16 v[74:77], v[122:125], v[160:163], v[74:77]
	v_mfma_f32_16x16x32_bf16 v[70:73], v[126:129], v[160:163], v[70:73]
	v_mfma_f32_16x16x32_bf16 v[66:69], v[156:159], v[160:163], v[66:69]
	s_waitcnt lgkmcnt(1)
	v_mfma_f32_16x16x32_bf16 v[62:65], v[114:117], v[180:183], v[62:65]
	ds_read_b128 v[164:167], v189 offset:49168
	ds_read_b128 v[168:171], v189 offset:49680
	v_mfma_f32_16x16x32_bf16 v[58:61], v[122:125], v[180:183], v[58:61]
	v_mfma_f32_16x16x32_bf16 v[54:57], v[126:129], v[180:183], v[54:57]
	ds_read_b128 v[172:175], v189 offset:53264
	ds_read_b128 v[176:179], v189 offset:53776
	v_mfma_f32_16x16x32_bf16 v[50:53], v[156:159], v[180:183], v[50:53]
	s_waitcnt lgkmcnt(4)
	v_mfma_f32_16x16x32_bf16 v[46:49], v[114:117], v[184:187], v[46:49]
	ds_read_b128 v[118:121], v113 offset:32768
	ds_read_b128 v[160:163], v113 offset:34816
	v_mfma_f32_16x16x32_bf16 v[42:45], v[122:125], v[184:187], v[42:45]
	v_mfma_f32_16x16x32_bf16 v[38:41], v[126:129], v[184:187], v[38:41]
	v_mfma_f32_16x16x32_bf16 v[34:37], v[156:159], v[184:187], v[34:37]
	s_waitcnt lgkmcnt(1)
	v_mfma_f32_16x16x32_bf16 v[94:97], v[164:167], v[118:121], v[94:97]
	v_mfma_f32_16x16x32_bf16 v[90:93], v[168:171], v[118:121], v[90:93]
	v_mfma_f32_16x16x32_bf16 v[86:89], v[172:175], v[118:121], v[86:89]
	v_mfma_f32_16x16x32_bf16 v[82:85], v[176:179], v[118:121], v[82:85]
	s_waitcnt lgkmcnt(0)
	v_mfma_f32_16x16x32_bf16 v[78:81], v[164:167], v[160:163], v[78:81]
	ds_read_b128 v[180:183], v113 offset:36864
	ds_read_b128 v[184:187], v113 offset:38912
	v_mfma_f32_16x16x32_bf16 v[74:77], v[168:171], v[160:163], v[74:77]
	v_mfma_f32_16x16x32_bf16 v[70:73], v[172:175], v[160:163], v[70:73]
	v_mfma_f32_16x16x32_bf16 v[66:69], v[176:179], v[160:163], v[66:69]
	s_waitcnt lgkmcnt(1)
	v_mfma_f32_16x16x32_bf16 v[62:65], v[164:167], v[180:183], v[62:65]
	v_mfma_f32_16x16x32_bf16 v[58:61], v[168:171], v[180:183], v[58:61]
	v_mfma_f32_16x16x32_bf16 v[54:57], v[172:175], v[180:183], v[54:57]
	v_mfma_f32_16x16x32_bf16 v[50:53], v[176:179], v[180:183], v[50:53]
	s_waitcnt lgkmcnt(0)
	v_mfma_f32_16x16x32_bf16 v[46:49], v[164:167], v[184:187], v[46:49]
	v_mfma_f32_16x16x32_bf16 v[42:45], v[168:171], v[184:187], v[42:45]
	v_mfma_f32_16x16x32_bf16 v[38:41], v[172:175], v[184:187], v[38:41]
	v_mfma_f32_16x16x32_bf16 v[34:37], v[176:179], v[184:187], v[34:37]
	s_setprio 0
	s_barrier
	s_branch .LBB0_1383
